# v5 + s_setprio pairs removed from the re-encoded P2/P8 K-loops (32 fewer scalar instrs per iteration)
# speedup vs baseline: 1.0074x; 1.0074x over previous
.LBB0_157:
	v_add_u32_e32 v140, s91, v180
	ds_read_b128 v[128:131], v140
	ds_read_b128 v[132:135], v140 offset:1024
	ds_read_b128 v[136:139], v140 offset:2048
	ds_read_b128 v[140:143], v140 offset:3072
	s_add_u32 s10, s8, 0xfff80080
	s_addc_u32 s11, s9, -1
	s_cmp_eq_u32 s74, 28
	s_cselect_b32 s73, s2, s11
	s_cselect_b32 s72, s13, s10
	s_cselect_b32 s11, s20, s71
	s_cselect_b32 s10, s63, s65
	s_add_i32 m0, s40, 0xc000
	ds_read_b128 v[144:147], v208
	ds_read_b128 v[172:175], v208 offset:1024
	ds_read_b128 v[176:179], v208 offset:2048
	ds_read_b128 v[212:215], v208 offset:3072
	global_load_lds_dwordx4 v166, s[8:9]
	s_add_i32 m0, s40, 0xe000
	ds_read_b128 v[216:219], v208 offset:4096
	ds_read_b128 v[220:223], v208 offset:5120
	ds_read_b128 v[224:227], v208 offset:6144
	ds_read_b128 v[228:231], v208 offset:7168
	global_load_lds_dwordx4 v168, s[8:9]
	s_waitcnt lgkmcnt(8)
	s_barrier
	s_waitcnt lgkmcnt(0)
	v_mfma_f32_16x16x32_bf16 v[124:127], v[128:131], v[144:147], v[124:127]
	v_mfma_f32_16x16x32_bf16 v[120:123], v[136:139], v[144:147], v[120:123]
	v_mfma_f32_16x16x32_bf16 v[108:111], v[128:131], v[176:179], v[108:111]
	v_mfma_f32_16x16x32_bf16 v[104:107], v[136:139], v[176:179], v[104:107]
	v_mfma_f32_16x16x32_bf16 v[92:95], v[128:131], v[216:219], v[92:95]
	v_mfma_f32_16x16x32_bf16 v[88:91], v[136:139], v[216:219], v[88:91]
	v_mfma_f32_16x16x32_bf16 v[76:79], v[128:131], v[224:227], v[76:79]
	v_mfma_f32_16x16x32_bf16 v[72:75], v[136:139], v[224:227], v[72:75]
	v_mfma_f32_16x16x32_bf16 v[124:127], v[132:135], v[172:175], v[124:127]
	v_mfma_f32_16x16x32_bf16 v[120:123], v[140:143], v[172:175], v[120:123]
	v_mfma_f32_16x16x32_bf16 v[108:111], v[132:135], v[212:215], v[108:111]
	v_mfma_f32_16x16x32_bf16 v[104:107], v[140:143], v[212:215], v[104:107]
	v_mfma_f32_16x16x32_bf16 v[92:95], v[132:135], v[220:223], v[92:95]
	v_mfma_f32_16x16x32_bf16 v[88:91], v[140:143], v[220:223], v[88:91]
	v_mfma_f32_16x16x32_bf16 v[76:79], v[132:135], v[228:231], v[76:79]
	v_mfma_f32_16x16x32_bf16 v[72:75], v[140:143], v[228:231], v[72:75]
	s_barrier
	v_add_u32_e32 v156, s92, v180
	s_add_i32 m0, s40, 0x10000
	ds_read_b128 v[232:235], v156
	ds_read_b128 v[236:239], v156 offset:1024
	global_load_lds_dwordx4 v150, s[10:11]
	s_add_i32 m0, s40, 0x12000
	ds_read_b128 v[240:243], v156 offset:2048
	ds_read_b128 v[244:247], v156 offset:3072
	global_load_lds_dwordx4 v154, s[10:11]
	s_barrier
	s_waitcnt lgkmcnt(0)
	v_mfma_f32_16x16x32_bf16 v[116:119], v[232:235], v[144:147], v[116:119]
	v_mfma_f32_16x16x32_bf16 v[112:115], v[240:243], v[144:147], v[112:115]
	v_mfma_f32_16x16x32_bf16 v[100:103], v[232:235], v[176:179], v[100:103]
	v_mfma_f32_16x16x32_bf16 v[96:99], v[240:243], v[176:179], v[96:99]
	v_mfma_f32_16x16x32_bf16 v[84:87], v[232:235], v[216:219], v[84:87]
	v_mfma_f32_16x16x32_bf16 v[80:83], v[240:243], v[216:219], v[80:83]
	v_mfma_f32_16x16x32_bf16 v[68:71], v[232:235], v[224:227], v[68:71]
	v_mfma_f32_16x16x32_bf16 v[64:67], v[240:243], v[224:227], v[64:67]
	v_mfma_f32_16x16x32_bf16 v[116:119], v[236:239], v[172:175], v[116:119]
	v_mfma_f32_16x16x32_bf16 v[112:115], v[244:247], v[172:175], v[112:115]
	v_mfma_f32_16x16x32_bf16 v[100:103], v[236:239], v[212:215], v[100:103]
	v_mfma_f32_16x16x32_bf16 v[96:99], v[244:247], v[212:215], v[96:99]
	v_mfma_f32_16x16x32_bf16 v[84:87], v[236:239], v[220:223], v[84:87]
	v_mfma_f32_16x16x32_bf16 v[80:83], v[244:247], v[220:223], v[80:83]
	v_mfma_f32_16x16x32_bf16 v[68:71], v[236:239], v[228:231], v[68:71]
	v_mfma_f32_16x16x32_bf16 v[64:67], v[244:247], v[228:231], v[64:67]
	s_barrier
	s_mov_b32 m0, s40
	ds_read_b128 v[144:147], v208 offset:16384
	ds_read_b128 v[172:175], v208 offset:17408
	ds_read_b128 v[176:179], v208 offset:18432
	ds_read_b128 v[212:215], v208 offset:19456
	global_load_lds_dwordx4 v148, s[72:73]
	s_mov_b32 m0, s41
	ds_read_b128 v[216:219], v208 offset:20480
	ds_read_b128 v[220:223], v208 offset:21504
	ds_read_b128 v[224:227], v208 offset:22528
	ds_read_b128 v[228:231], v208 offset:23552
	global_load_lds_dwordx4 v152, s[72:73]
	s_barrier
	s_waitcnt lgkmcnt(0)
	v_mfma_f32_16x16x32_bf16 v[60:63], v[128:131], v[144:147], v[60:63]
	v_mfma_f32_16x16x32_bf16 v[56:59], v[136:139], v[144:147], v[56:59]
	v_mfma_f32_16x16x32_bf16 v[44:47], v[128:131], v[176:179], v[44:47]
	v_mfma_f32_16x16x32_bf16 v[40:43], v[136:139], v[176:179], v[40:43]
	v_mfma_f32_16x16x32_bf16 v[28:31], v[128:131], v[216:219], v[28:31]
	v_mfma_f32_16x16x32_bf16 v[24:27], v[136:139], v[216:219], v[24:27]
	v_mfma_f32_16x16x32_bf16 v[12:15], v[128:131], v[224:227], v[12:15]
	v_mfma_f32_16x16x32_bf16 v[8:11], v[136:139], v[224:227], v[8:11]
	v_mfma_f32_16x16x32_bf16 v[60:63], v[132:135], v[172:175], v[60:63]
	v_mfma_f32_16x16x32_bf16 v[56:59], v[140:143], v[172:175], v[56:59]
	v_mfma_f32_16x16x32_bf16 v[44:47], v[132:135], v[212:215], v[44:47]
	v_mfma_f32_16x16x32_bf16 v[40:43], v[140:143], v[212:215], v[40:43]
	v_mfma_f32_16x16x32_bf16 v[28:31], v[132:135], v[220:223], v[28:31]
	v_mfma_f32_16x16x32_bf16 v[24:27], v[140:143], v[220:223], v[24:27]
	v_mfma_f32_16x16x32_bf16 v[12:15], v[132:135], v[228:231], v[12:15]
	v_mfma_f32_16x16x32_bf16 v[8:11], v[140:143], v[228:231], v[8:11]
	s_barrier
	s_add_u32 s34, s10, 0x80000
	s_addc_u32 s35, s11, 0
	s_add_i32 m0, s40, 0x14000
	s_nop 0
	global_load_lds_dwordx4 v150, s[34:35]
	s_add_i32 m0, s40, 0x16000
	s_nop 0
	global_load_lds_dwordx4 v154, s[34:35]
	s_waitcnt vmcnt(6)
	s_barrier
	v_mfma_f32_16x16x32_bf16 v[52:55], v[232:235], v[144:147], v[52:55]
	v_mfma_f32_16x16x32_bf16 v[48:51], v[240:243], v[144:147], v[48:51]
	v_mfma_f32_16x16x32_bf16 v[36:39], v[232:235], v[176:179], v[36:39]
	v_mfma_f32_16x16x32_bf16 v[32:35], v[240:243], v[176:179], v[32:35]
	v_mfma_f32_16x16x32_bf16 v[20:23], v[232:235], v[216:219], v[20:23]
	v_mfma_f32_16x16x32_bf16 v[16:19], v[240:243], v[216:219], v[16:19]
	v_mfma_f32_16x16x32_bf16 v[4:7], v[232:235], v[224:227], v[4:7]
	v_mfma_f32_16x16x32_bf16 v[0:3], v[240:243], v[224:227], v[0:3]
	v_mfma_f32_16x16x32_bf16 v[52:55], v[236:239], v[172:175], v[52:55]
	v_mfma_f32_16x16x32_bf16 v[48:51], v[244:247], v[172:175], v[48:51]
	v_mfma_f32_16x16x32_bf16 v[36:39], v[236:239], v[212:215], v[36:39]
	v_mfma_f32_16x16x32_bf16 v[32:35], v[244:247], v[212:215], v[32:35]
	v_mfma_f32_16x16x32_bf16 v[20:23], v[236:239], v[220:223], v[20:23]
	v_mfma_f32_16x16x32_bf16 v[16:19], v[244:247], v[220:223], v[16:19]
	v_mfma_f32_16x16x32_bf16 v[4:7], v[236:239], v[228:231], v[4:7]
	v_mfma_f32_16x16x32_bf16 v[0:3], v[244:247], v[228:231], v[0:3]
	s_barrier
	s_add_i32 s75, 0, 0x18000
	v_add_u32_e32 v140, s75, v180
	ds_read_b128 v[128:131], v140
	ds_read_b128 v[132:135], v140 offset:1024
	ds_read_b128 v[136:139], v140 offset:2048
	ds_read_b128 v[140:143], v140 offset:3072
	s_add_u32 s34, s72, 0x80000
	s_addc_u32 s35, s73, 0
	s_mov_b32 m0, s82
	ds_read_b128 v[144:147], v208 offset:32768
	ds_read_b128 v[172:175], v208 offset:33792
	ds_read_b128 v[176:179], v208 offset:34816
	ds_read_b128 v[212:215], v208 offset:35840
	global_load_lds_dwordx4 v148, s[34:35]
	s_mov_b32 m0, s83
	ds_read_b128 v[216:219], v208 offset:36864
	ds_read_b128 v[220:223], v208 offset:37888
	ds_read_b128 v[224:227], v208 offset:38912
	ds_read_b128 v[228:231], v208 offset:39936
	global_load_lds_dwordx4 v152, s[34:35]
	s_waitcnt lgkmcnt(8)
	s_barrier
	s_waitcnt lgkmcnt(0)
	v_mfma_f32_16x16x32_bf16 v[124:127], v[128:131], v[144:147], v[124:127]
	v_mfma_f32_16x16x32_bf16 v[120:123], v[136:139], v[144:147], v[120:123]
	v_mfma_f32_16x16x32_bf16 v[108:111], v[128:131], v[176:179], v[108:111]
	v_mfma_f32_16x16x32_bf16 v[104:107], v[136:139], v[176:179], v[104:107]
	v_mfma_f32_16x16x32_bf16 v[92:95], v[128:131], v[216:219], v[92:95]
	v_mfma_f32_16x16x32_bf16 v[88:91], v[136:139], v[216:219], v[88:91]
	v_mfma_f32_16x16x32_bf16 v[76:79], v[128:131], v[224:227], v[76:79]
	v_mfma_f32_16x16x32_bf16 v[72:75], v[136:139], v[224:227], v[72:75]
	v_mfma_f32_16x16x32_bf16 v[124:127], v[132:135], v[172:175], v[124:127]
	v_mfma_f32_16x16x32_bf16 v[120:123], v[140:143], v[172:175], v[120:123]
	v_mfma_f32_16x16x32_bf16 v[108:111], v[132:135], v[212:215], v[108:111]
	v_mfma_f32_16x16x32_bf16 v[104:107], v[140:143], v[212:215], v[104:107]
	v_mfma_f32_16x16x32_bf16 v[92:95], v[132:135], v[220:223], v[92:95]
	v_mfma_f32_16x16x32_bf16 v[88:91], v[140:143], v[220:223], v[88:91]
	v_mfma_f32_16x16x32_bf16 v[76:79], v[132:135], v[228:231], v[76:79]
	v_mfma_f32_16x16x32_bf16 v[72:75], v[140:143], v[228:231], v[72:75]
	s_barrier
	s_add_i32 s34, 0, 0x1c000
	v_add_u32_e32 v156, s34, v180
	s_add_u32 s34, s10, 0x80
	s_addc_u32 s35, s11, 0
	s_add_i32 m0, s40, 0x18000
	ds_read_b128 v[232:235], v156
	ds_read_b128 v[236:239], v156 offset:1024
	global_load_lds_dwordx4 v150, s[34:35]
	s_add_i32 m0, s40, 0x1a000
	ds_read_b128 v[240:243], v156 offset:2048
	ds_read_b128 v[244:247], v156 offset:3072
	global_load_lds_dwordx4 v154, s[34:35]
	s_barrier
	s_waitcnt lgkmcnt(0)
	v_mfma_f32_16x16x32_bf16 v[116:119], v[232:235], v[144:147], v[116:119]
	v_mfma_f32_16x16x32_bf16 v[112:115], v[240:243], v[144:147], v[112:115]
	v_mfma_f32_16x16x32_bf16 v[100:103], v[232:235], v[176:179], v[100:103]
	v_mfma_f32_16x16x32_bf16 v[96:99], v[240:243], v[176:179], v[96:99]
	v_mfma_f32_16x16x32_bf16 v[84:87], v[232:235], v[216:219], v[84:87]
	v_mfma_f32_16x16x32_bf16 v[80:83], v[240:243], v[216:219], v[80:83]
	v_mfma_f32_16x16x32_bf16 v[68:71], v[232:235], v[224:227], v[68:71]
	v_mfma_f32_16x16x32_bf16 v[64:67], v[240:243], v[224:227], v[64:67]
	v_mfma_f32_16x16x32_bf16 v[116:119], v[236:239], v[172:175], v[116:119]
	v_mfma_f32_16x16x32_bf16 v[112:115], v[244:247], v[172:175], v[112:115]
	v_mfma_f32_16x16x32_bf16 v[100:103], v[236:239], v[212:215], v[100:103]
	v_mfma_f32_16x16x32_bf16 v[96:99], v[244:247], v[212:215], v[96:99]
	v_mfma_f32_16x16x32_bf16 v[84:87], v[236:239], v[220:223], v[84:87]
	v_mfma_f32_16x16x32_bf16 v[80:83], v[244:247], v[220:223], v[80:83]
	v_mfma_f32_16x16x32_bf16 v[68:71], v[236:239], v[228:231], v[68:71]
	v_mfma_f32_16x16x32_bf16 v[64:67], v[244:247], v[228:231], v[64:67]
	s_barrier
	s_add_u32 s34, s72, 0x80
	s_addc_u32 s35, s73, 0
	s_mov_b32 m0, s87
	ds_read_b128 v[144:147], v208 offset:49152
	ds_read_b128 v[172:175], v208 offset:50176
	ds_read_b128 v[176:179], v208 offset:51200
	ds_read_b128 v[212:215], v208 offset:52224
	global_load_lds_dwordx4 v148, s[34:35]
	s_mov_b32 m0, s88
	ds_read_b128 v[216:219], v208 offset:53248
	ds_read_b128 v[220:223], v208 offset:54272
	ds_read_b128 v[224:227], v208 offset:55296
	ds_read_b128 v[228:231], v208 offset:56320
	global_load_lds_dwordx4 v152, s[34:35]
	s_barrier
	s_waitcnt lgkmcnt(0)
	v_mfma_f32_16x16x32_bf16 v[60:63], v[128:131], v[144:147], v[60:63]
	v_mfma_f32_16x16x32_bf16 v[56:59], v[136:139], v[144:147], v[56:59]
	v_mfma_f32_16x16x32_bf16 v[44:47], v[128:131], v[176:179], v[44:47]
	v_mfma_f32_16x16x32_bf16 v[40:43], v[136:139], v[176:179], v[40:43]
	v_mfma_f32_16x16x32_bf16 v[28:31], v[128:131], v[216:219], v[28:31]
	v_mfma_f32_16x16x32_bf16 v[24:27], v[136:139], v[216:219], v[24:27]
	v_mfma_f32_16x16x32_bf16 v[12:15], v[128:131], v[224:227], v[12:15]
	v_mfma_f32_16x16x32_bf16 v[8:11], v[136:139], v[224:227], v[8:11]
	v_mfma_f32_16x16x32_bf16 v[60:63], v[132:135], v[172:175], v[60:63]
	v_mfma_f32_16x16x32_bf16 v[56:59], v[140:143], v[172:175], v[56:59]
	v_mfma_f32_16x16x32_bf16 v[44:47], v[132:135], v[212:215], v[44:47]
	v_mfma_f32_16x16x32_bf16 v[40:43], v[140:143], v[212:215], v[40:43]
	v_mfma_f32_16x16x32_bf16 v[28:31], v[132:135], v[220:223], v[28:31]
	v_mfma_f32_16x16x32_bf16 v[24:27], v[140:143], v[220:223], v[24:27]
	v_mfma_f32_16x16x32_bf16 v[12:15], v[132:135], v[228:231], v[12:15]
	v_mfma_f32_16x16x32_bf16 v[8:11], v[140:143], v[228:231], v[8:11]
	s_barrier
	s_add_u32 s34, s10, 0x80080
	s_addc_u32 s35, s11, 0
	s_add_i32 m0, s40, 0x1c000
	s_nop 0
	global_load_lds_dwordx4 v150, s[34:35]
	s_add_i32 m0, s40, 0x1e000
	s_nop 0
	global_load_lds_dwordx4 v154, s[34:35]
	s_waitcnt vmcnt(6)
	s_barrier
	v_mfma_f32_16x16x32_bf16 v[52:55], v[232:235], v[144:147], v[52:55]
	v_mfma_f32_16x16x32_bf16 v[48:51], v[240:243], v[144:147], v[48:51]
	v_mfma_f32_16x16x32_bf16 v[36:39], v[232:235], v[176:179], v[36:39]
	v_mfma_f32_16x16x32_bf16 v[32:35], v[240:243], v[176:179], v[32:35]
	v_mfma_f32_16x16x32_bf16 v[20:23], v[232:235], v[216:219], v[20:23]
	v_mfma_f32_16x16x32_bf16 v[16:19], v[240:243], v[216:219], v[16:19]
	v_mfma_f32_16x16x32_bf16 v[4:7], v[232:235], v[224:227], v[4:7]
	v_mfma_f32_16x16x32_bf16 v[0:3], v[240:243], v[224:227], v[0:3]
	v_mfma_f32_16x16x32_bf16 v[52:55], v[236:239], v[172:175], v[52:55]
	v_mfma_f32_16x16x32_bf16 v[48:51], v[244:247], v[172:175], v[48:51]
	v_mfma_f32_16x16x32_bf16 v[36:39], v[236:239], v[212:215], v[36:39]
	v_mfma_f32_16x16x32_bf16 v[32:35], v[244:247], v[212:215], v[32:35]
	v_mfma_f32_16x16x32_bf16 v[20:23], v[236:239], v[220:223], v[20:23]
	v_mfma_f32_16x16x32_bf16 v[16:19], v[244:247], v[220:223], v[16:19]
	v_mfma_f32_16x16x32_bf16 v[4:7], v[236:239], v[228:231], v[4:7]
	v_mfma_f32_16x16x32_bf16 v[0:3], v[244:247], v[228:231], v[0:3]
	s_add_i32 s74, s74, 2
	s_add_u32 s8, s8, 0x100
	s_addc_u32 s9, s9, 0
	s_add_u32 s65, s65, 0x100
	s_addc_u32 s71, s71, 0
	s_cmp_gt_u32 s74, 29
	s_barrier
	s_cbranch_scc0 .LBB0_157
	s_cmp_gt_i32 s70, 15
	s_cselect_b64 s[74:75], -1, 0
	s_cmp_lt_i32 s70, 16
	s_cselect_b64 s[72:73], -1, 0
	s_cmp_gt_i32 s12, 9
	s_mov_b64 s[8:9], -1
	s_cbranch_scc0 .LBB0_338
	s_cmp_gt_u32 s12, 11
	s_cbranch_scc0 .LBB0_272
	s_cmp_gt_u32 s12, 19
	s_mov_b64 s[80:81], -1
	s_cbranch_scc0 .LBB0_173
	s_cmp_gt_u32 s12, 27
	s_cbranch_scc0 .LBB0_170
	s_lshl_b32 s2, s12, 8
	s_cmp_gt_u32 s12, 35
	s_mov_b64 s[8:9], -1
	s_mov_b64 s[78:79], -1
	s_cbranch_scc0 .LBB0_168
	s_cmp_gt_u32 s12, 43
	s_mov_b64 s[10:11], -1
	s_cbranch_scc0 .LBB0_165
	s_add_i32 s20, s2, 0xffffd400
	s_mov_b64 s[10:11], 0

.LBB0_1065:
	ds_read_b128 v[152:155], v148
	ds_read_b128 v[156:159], v148 offset:1024
	ds_read_b128 v[160:163], v148 offset:2048
	ds_read_b128 v[164:167], v148 offset:3072
	s_add_u32 s28, s26, 0xfff80080
	s_addc_u32 s29, s27, -1
	s_cmp_eq_u32 s59, 28
	s_cselect_b32 s31, s15, s29
	s_cselect_b32 s30, s25, s28
	s_cselect_b32 s29, s17, s58
	s_cselect_b32 s28, s56, s57
	s_add_i32 m0, s47, 0xc000
	ds_read_b128 v[168:171], v149
	ds_read_b128 v[172:175], v149 offset:1024
	ds_read_b128 v[176:179], v149 offset:2048
	ds_read_b128 v[180:183], v149 offset:3072
	global_load_lds_dwordx4 v138, s[26:27]
	s_add_i32 m0, s47, 0xe000
	ds_read_b128 v[186:189], v149 offset:4096
	ds_read_b128 v[190:193], v149 offset:5120
	ds_read_b128 v[194:197], v149 offset:6144
	ds_read_b128 v[198:201], v149 offset:7168
	global_load_lds_dwordx4 v140, s[26:27]
	s_waitcnt lgkmcnt(8)
	s_barrier
	s_waitcnt lgkmcnt(0)
	v_mfma_f32_16x16x32_bf16 v[124:127], v[152:155], v[168:171], v[124:127]
	v_mfma_f32_16x16x32_bf16 v[120:123], v[160:163], v[168:171], v[120:123]
	v_mfma_f32_16x16x32_bf16 v[108:111], v[152:155], v[176:179], v[108:111]
	v_mfma_f32_16x16x32_bf16 v[104:107], v[160:163], v[176:179], v[104:107]
	v_mfma_f32_16x16x32_bf16 v[92:95], v[152:155], v[186:189], v[92:95]
	v_mfma_f32_16x16x32_bf16 v[88:91], v[160:163], v[186:189], v[88:91]
	v_mfma_f32_16x16x32_bf16 v[76:79], v[152:155], v[194:197], v[76:79]
	v_mfma_f32_16x16x32_bf16 v[72:75], v[160:163], v[194:197], v[72:75]
	v_mfma_f32_16x16x32_bf16 v[124:127], v[156:159], v[172:175], v[124:127]
	v_mfma_f32_16x16x32_bf16 v[120:123], v[164:167], v[172:175], v[120:123]
	v_mfma_f32_16x16x32_bf16 v[108:111], v[156:159], v[180:183], v[108:111]
	v_mfma_f32_16x16x32_bf16 v[104:107], v[164:167], v[180:183], v[104:107]
	v_mfma_f32_16x16x32_bf16 v[92:95], v[156:159], v[190:193], v[92:95]
	v_mfma_f32_16x16x32_bf16 v[88:91], v[164:167], v[190:193], v[88:91]
	v_mfma_f32_16x16x32_bf16 v[76:79], v[156:159], v[198:201], v[76:79]
	v_mfma_f32_16x16x32_bf16 v[72:75], v[164:167], v[198:201], v[72:75]
	s_barrier
	s_add_i32 m0, s47, 0x10000
	ds_read_b128 v[202:205], v150
	ds_read_b128 v[206:209], v150 offset:1024
	global_load_lds_dwordx4 v132, s[28:29]
	s_add_i32 m0, s47, 0x12000
	ds_read_b128 v[210:213], v150 offset:2048
	ds_read_b128 v[214:217], v150 offset:3072
	global_load_lds_dwordx4 v128, s[28:29]
	s_barrier
	s_waitcnt lgkmcnt(0)
	v_mfma_f32_16x16x32_bf16 v[116:119], v[202:205], v[168:171], v[116:119]
	v_mfma_f32_16x16x32_bf16 v[112:115], v[210:213], v[168:171], v[112:115]
	v_mfma_f32_16x16x32_bf16 v[100:103], v[202:205], v[176:179], v[100:103]
	v_mfma_f32_16x16x32_bf16 v[96:99], v[210:213], v[176:179], v[96:99]
	v_mfma_f32_16x16x32_bf16 v[84:87], v[202:205], v[186:189], v[84:87]
	v_mfma_f32_16x16x32_bf16 v[80:83], v[210:213], v[186:189], v[80:83]
	v_mfma_f32_16x16x32_bf16 v[68:71], v[202:205], v[194:197], v[68:71]
	v_mfma_f32_16x16x32_bf16 v[64:67], v[210:213], v[194:197], v[64:67]
	v_mfma_f32_16x16x32_bf16 v[116:119], v[206:209], v[172:175], v[116:119]
	v_mfma_f32_16x16x32_bf16 v[112:115], v[214:217], v[172:175], v[112:115]
	v_mfma_f32_16x16x32_bf16 v[100:103], v[206:209], v[180:183], v[100:103]
	v_mfma_f32_16x16x32_bf16 v[96:99], v[214:217], v[180:183], v[96:99]
	v_mfma_f32_16x16x32_bf16 v[84:87], v[206:209], v[190:193], v[84:87]
	v_mfma_f32_16x16x32_bf16 v[80:83], v[214:217], v[190:193], v[80:83]
	v_mfma_f32_16x16x32_bf16 v[68:71], v[206:209], v[198:201], v[68:71]
	v_mfma_f32_16x16x32_bf16 v[64:67], v[214:217], v[198:201], v[64:67]
	s_barrier
	s_mov_b32 m0, s47
	ds_read_b128 v[168:171], v149 offset:16384
	ds_read_b128 v[172:175], v149 offset:17408
	ds_read_b128 v[176:179], v149 offset:18432
	ds_read_b128 v[180:183], v149 offset:19456
	global_load_lds_dwordx4 v134, s[30:31]
	s_mov_b32 m0, s48
	ds_read_b128 v[186:189], v149 offset:20480
	ds_read_b128 v[190:193], v149 offset:21504
	ds_read_b128 v[194:197], v149 offset:22528
	ds_read_b128 v[198:201], v149 offset:23552
	global_load_lds_dwordx4 v130, s[30:31]
	s_barrier
	s_waitcnt lgkmcnt(0)
	v_mfma_f32_16x16x32_bf16 v[60:63], v[152:155], v[168:171], v[60:63]
	v_mfma_f32_16x16x32_bf16 v[56:59], v[160:163], v[168:171], v[56:59]
	v_mfma_f32_16x16x32_bf16 v[44:47], v[152:155], v[176:179], v[44:47]
	v_mfma_f32_16x16x32_bf16 v[40:43], v[160:163], v[176:179], v[40:43]
	v_mfma_f32_16x16x32_bf16 v[28:31], v[152:155], v[186:189], v[28:31]
	v_mfma_f32_16x16x32_bf16 v[24:27], v[160:163], v[186:189], v[24:27]
	v_mfma_f32_16x16x32_bf16 v[12:15], v[152:155], v[194:197], v[12:15]
	v_mfma_f32_16x16x32_bf16 v[8:11], v[160:163], v[194:197], v[8:11]
	v_mfma_f32_16x16x32_bf16 v[60:63], v[156:159], v[172:175], v[60:63]
	v_mfma_f32_16x16x32_bf16 v[56:59], v[164:167], v[172:175], v[56:59]
	v_mfma_f32_16x16x32_bf16 v[44:47], v[156:159], v[180:183], v[44:47]
	v_mfma_f32_16x16x32_bf16 v[40:43], v[164:167], v[180:183], v[40:43]
	v_mfma_f32_16x16x32_bf16 v[28:31], v[156:159], v[190:193], v[28:31]
	v_mfma_f32_16x16x32_bf16 v[24:27], v[164:167], v[190:193], v[24:27]
	v_mfma_f32_16x16x32_bf16 v[12:15], v[156:159], v[198:201], v[12:15]
	v_mfma_f32_16x16x32_bf16 v[8:11], v[164:167], v[198:201], v[8:11]
	s_barrier
	s_add_u32 s34, s28, 0x80000
	s_addc_u32 s35, s29, 0
	s_add_i32 m0, s47, 0x14000
	s_nop 0
	global_load_lds_dwordx4 v132, s[34:35]
	s_add_i32 m0, s47, 0x16000
	s_nop 0
	global_load_lds_dwordx4 v128, s[34:35]
	s_waitcnt vmcnt(6)
	s_barrier
	v_mfma_f32_16x16x32_bf16 v[52:55], v[202:205], v[168:171], v[52:55]
	v_mfma_f32_16x16x32_bf16 v[48:51], v[210:213], v[168:171], v[48:51]
	v_mfma_f32_16x16x32_bf16 v[36:39], v[202:205], v[176:179], v[36:39]
	v_mfma_f32_16x16x32_bf16 v[32:35], v[210:213], v[176:179], v[32:35]
	v_mfma_f32_16x16x32_bf16 v[20:23], v[202:205], v[186:189], v[20:23]
	v_mfma_f32_16x16x32_bf16 v[16:19], v[210:213], v[186:189], v[16:19]
	v_mfma_f32_16x16x32_bf16 v[4:7], v[202:205], v[194:197], v[4:7]
	v_mfma_f32_16x16x32_bf16 v[0:3], v[210:213], v[194:197], v[0:3]
	v_mfma_f32_16x16x32_bf16 v[52:55], v[206:209], v[172:175], v[52:55]
	v_mfma_f32_16x16x32_bf16 v[48:51], v[214:217], v[172:175], v[48:51]
	v_mfma_f32_16x16x32_bf16 v[36:39], v[206:209], v[180:183], v[36:39]
	v_mfma_f32_16x16x32_bf16 v[32:35], v[214:217], v[180:183], v[32:35]
	v_mfma_f32_16x16x32_bf16 v[20:23], v[206:209], v[190:193], v[20:23]
	v_mfma_f32_16x16x32_bf16 v[16:19], v[214:217], v[190:193], v[16:19]
	v_mfma_f32_16x16x32_bf16 v[4:7], v[206:209], v[198:201], v[4:7]
	v_mfma_f32_16x16x32_bf16 v[0:3], v[214:217], v[198:201], v[0:3]
	s_barrier
	s_add_i32 s34, 0, 0x18000
	v_add_u32_e32 v151, s34, v147
	ds_read_b128 v[152:155], v151
	ds_read_b128 v[156:159], v151 offset:1024
	ds_read_b128 v[160:163], v151 offset:2048
	ds_read_b128 v[164:167], v151 offset:3072
	s_add_u32 s34, s30, 0x80000
	s_addc_u32 s35, s31, 0
	s_mov_b32 m0, s49
	ds_read_b128 v[168:171], v149 offset:32768
	ds_read_b128 v[172:175], v149 offset:33792
	ds_read_b128 v[176:179], v149 offset:34816
	ds_read_b128 v[180:183], v149 offset:35840
	global_load_lds_dwordx4 v134, s[34:35]
	s_mov_b32 m0, s50
	ds_read_b128 v[186:189], v149 offset:36864
	ds_read_b128 v[190:193], v149 offset:37888
	ds_read_b128 v[194:197], v149 offset:38912
	ds_read_b128 v[198:201], v149 offset:39936
	global_load_lds_dwordx4 v130, s[34:35]
	s_waitcnt lgkmcnt(8)
	s_barrier
	s_waitcnt lgkmcnt(0)
	v_mfma_f32_16x16x32_bf16 v[124:127], v[152:155], v[168:171], v[124:127]
	v_mfma_f32_16x16x32_bf16 v[120:123], v[160:163], v[168:171], v[120:123]
	v_mfma_f32_16x16x32_bf16 v[108:111], v[152:155], v[176:179], v[108:111]
	v_mfma_f32_16x16x32_bf16 v[104:107], v[160:163], v[176:179], v[104:107]
	v_mfma_f32_16x16x32_bf16 v[92:95], v[152:155], v[186:189], v[92:95]
	v_mfma_f32_16x16x32_bf16 v[88:91], v[160:163], v[186:189], v[88:91]
	v_mfma_f32_16x16x32_bf16 v[76:79], v[152:155], v[194:197], v[76:79]
	v_mfma_f32_16x16x32_bf16 v[72:75], v[160:163], v[194:197], v[72:75]
	v_mfma_f32_16x16x32_bf16 v[124:127], v[156:159], v[172:175], v[124:127]
	v_mfma_f32_16x16x32_bf16 v[120:123], v[164:167], v[172:175], v[120:123]
	v_mfma_f32_16x16x32_bf16 v[108:111], v[156:159], v[180:183], v[108:111]
	v_mfma_f32_16x16x32_bf16 v[104:107], v[164:167], v[180:183], v[104:107]
	v_mfma_f32_16x16x32_bf16 v[92:95], v[156:159], v[190:193], v[92:95]
	v_mfma_f32_16x16x32_bf16 v[88:91], v[164:167], v[190:193], v[88:91]
	v_mfma_f32_16x16x32_bf16 v[76:79], v[156:159], v[198:201], v[76:79]
	v_mfma_f32_16x16x32_bf16 v[72:75], v[164:167], v[198:201], v[72:75]
	s_barrier
	s_add_i32 s34, 0, 0x1c000
	v_add_u32_e32 v151, s34, v147
	s_add_u32 s34, s28, 0x80
	s_addc_u32 s35, s29, 0
	s_add_i32 m0, s47, 0x18000
	ds_read_b128 v[202:205], v151
	ds_read_b128 v[206:209], v151 offset:1024
	global_load_lds_dwordx4 v132, s[34:35]
	s_add_i32 m0, s47, 0x1a000
	ds_read_b128 v[210:213], v151 offset:2048
	ds_read_b128 v[214:217], v151 offset:3072
	global_load_lds_dwordx4 v128, s[34:35]
	s_barrier
	s_waitcnt lgkmcnt(0)
	v_mfma_f32_16x16x32_bf16 v[116:119], v[202:205], v[168:171], v[116:119]
	v_mfma_f32_16x16x32_bf16 v[112:115], v[210:213], v[168:171], v[112:115]
	v_mfma_f32_16x16x32_bf16 v[100:103], v[202:205], v[176:179], v[100:103]
	v_mfma_f32_16x16x32_bf16 v[96:99], v[210:213], v[176:179], v[96:99]
	v_mfma_f32_16x16x32_bf16 v[84:87], v[202:205], v[186:189], v[84:87]
	v_mfma_f32_16x16x32_bf16 v[80:83], v[210:213], v[186:189], v[80:83]
	v_mfma_f32_16x16x32_bf16 v[68:71], v[202:205], v[194:197], v[68:71]
	v_mfma_f32_16x16x32_bf16 v[64:67], v[210:213], v[194:197], v[64:67]
	v_mfma_f32_16x16x32_bf16 v[116:119], v[206:209], v[172:175], v[116:119]
	v_mfma_f32_16x16x32_bf16 v[112:115], v[214:217], v[172:175], v[112:115]
	v_mfma_f32_16x16x32_bf16 v[100:103], v[206:209], v[180:183], v[100:103]
	v_mfma_f32_16x16x32_bf16 v[96:99], v[214:217], v[180:183], v[96:99]
	v_mfma_f32_16x16x32_bf16 v[84:87], v[206:209], v[190:193], v[84:87]
	v_mfma_f32_16x16x32_bf16 v[80:83], v[214:217], v[190:193], v[80:83]
	v_mfma_f32_16x16x32_bf16 v[68:71], v[206:209], v[198:201], v[68:71]
	v_mfma_f32_16x16x32_bf16 v[64:67], v[214:217], v[198:201], v[64:67]
	s_barrier
	s_add_u32 s34, s30, 0x80
	s_addc_u32 s35, s31, 0
	s_mov_b32 m0, s51
	ds_read_b128 v[168:171], v149 offset:49152
	ds_read_b128 v[172:175], v149 offset:50176
	ds_read_b128 v[176:179], v149 offset:51200
	ds_read_b128 v[180:183], v149 offset:52224
	global_load_lds_dwordx4 v134, s[34:35]
	s_mov_b32 m0, s52
	ds_read_b128 v[186:189], v149 offset:53248
	ds_read_b128 v[190:193], v149 offset:54272
	ds_read_b128 v[194:197], v149 offset:55296
	ds_read_b128 v[198:201], v149 offset:56320
	global_load_lds_dwordx4 v130, s[34:35]
	s_barrier
	s_waitcnt lgkmcnt(0)
	v_mfma_f32_16x16x32_bf16 v[60:63], v[152:155], v[168:171], v[60:63]
	v_mfma_f32_16x16x32_bf16 v[56:59], v[160:163], v[168:171], v[56:59]
	v_mfma_f32_16x16x32_bf16 v[44:47], v[152:155], v[176:179], v[44:47]
	v_mfma_f32_16x16x32_bf16 v[40:43], v[160:163], v[176:179], v[40:43]
	v_mfma_f32_16x16x32_bf16 v[28:31], v[152:155], v[186:189], v[28:31]
	v_mfma_f32_16x16x32_bf16 v[24:27], v[160:163], v[186:189], v[24:27]
	v_mfma_f32_16x16x32_bf16 v[12:15], v[152:155], v[194:197], v[12:15]
	v_mfma_f32_16x16x32_bf16 v[8:11], v[160:163], v[194:197], v[8:11]
	v_mfma_f32_16x16x32_bf16 v[60:63], v[156:159], v[172:175], v[60:63]
	v_mfma_f32_16x16x32_bf16 v[56:59], v[164:167], v[172:175], v[56:59]
	v_mfma_f32_16x16x32_bf16 v[44:47], v[156:159], v[180:183], v[44:47]
	v_mfma_f32_16x16x32_bf16 v[40:43], v[164:167], v[180:183], v[40:43]
	v_mfma_f32_16x16x32_bf16 v[28:31], v[156:159], v[190:193], v[28:31]
	v_mfma_f32_16x16x32_bf16 v[24:27], v[164:167], v[190:193], v[24:27]
	v_mfma_f32_16x16x32_bf16 v[12:15], v[156:159], v[198:201], v[12:15]
	v_mfma_f32_16x16x32_bf16 v[8:11], v[164:167], v[198:201], v[8:11]
	s_barrier
	s_add_u32 s34, s28, 0x80080
	s_addc_u32 s35, s29, 0
	s_add_i32 m0, s47, 0x1c000
	s_nop 0
	global_load_lds_dwordx4 v132, s[34:35]
	s_add_i32 m0, s47, 0x1e000
	s_nop 0
	global_load_lds_dwordx4 v128, s[34:35]
	s_waitcnt vmcnt(6)
	s_barrier
	v_mfma_f32_16x16x32_bf16 v[52:55], v[202:205], v[168:171], v[52:55]
	v_mfma_f32_16x16x32_bf16 v[48:51], v[210:213], v[168:171], v[48:51]
	v_mfma_f32_16x16x32_bf16 v[36:39], v[202:205], v[176:179], v[36:39]
	v_mfma_f32_16x16x32_bf16 v[32:35], v[210:213], v[176:179], v[32:35]
	v_mfma_f32_16x16x32_bf16 v[20:23], v[202:205], v[186:189], v[20:23]
	v_mfma_f32_16x16x32_bf16 v[16:19], v[210:213], v[186:189], v[16:19]
	v_mfma_f32_16x16x32_bf16 v[4:7], v[202:205], v[194:197], v[4:7]
	v_mfma_f32_16x16x32_bf16 v[0:3], v[210:213], v[194:197], v[0:3]
	v_mfma_f32_16x16x32_bf16 v[52:55], v[206:209], v[172:175], v[52:55]
	v_mfma_f32_16x16x32_bf16 v[48:51], v[214:217], v[172:175], v[48:51]
	v_mfma_f32_16x16x32_bf16 v[36:39], v[206:209], v[180:183], v[36:39]
	v_mfma_f32_16x16x32_bf16 v[32:35], v[214:217], v[180:183], v[32:35]
	v_mfma_f32_16x16x32_bf16 v[20:23], v[206:209], v[190:193], v[20:23]
	v_mfma_f32_16x16x32_bf16 v[16:19], v[214:217], v[190:193], v[16:19]
	v_mfma_f32_16x16x32_bf16 v[4:7], v[206:209], v[198:201], v[4:7]
	v_mfma_f32_16x16x32_bf16 v[0:3], v[214:217], v[198:201], v[0:3]
	s_add_i32 s59, s59, 2
	s_add_u32 s26, s26, 0x100
	s_addc_u32 s27, s27, 0
	s_add_u32 s57, s57, 0x100
	s_addc_u32 s58, s58, 0
	s_cmp_gt_u32 s59, 29
	s_barrier
	s_cbranch_scc0 .LBB0_1065
	v_mul_f32_e32 v154, 0xbfb8aa3b, v124
	v_exp_f32_e32 v154, v154
	v_mul_f32_e32 v155, 0xbfb8aa3b, v125
	v_exp_f32_e32 v155, v155
	v_lshl_add_u32 v151, s24, 8, v146
	v_add_f32_e32 v154, 1.0, v154
	v_rcp_f32_e32 v154, v154
	v_add_f32_e32 v155, 1.0, v155
	v_rcp_f32_e32 v155, v155
	s_lshl_b32 s24, s13, 7
	v_mul_f32_e32 v124, v124, v154
	v_mul_f32_e32 v120, v120, v124
	v_mul_f32_e32 v124, v125, v155
	v_mul_f32_e32 v125, 0xbfb8aa3b, v126
	v_exp_f32_e32 v125, v125
	v_mul_f32_e32 v154, 0xbfb8aa3b, v127
	v_exp_f32_e32 v154, v154
	v_mul_f32_e32 v121, v121, v124
	v_add_f32_e32 v124, 1.0, v125
	v_rcp_f32_e32 v124, v124
	v_add_f32_e32 v125, 1.0, v154
	v_rcp_f32_e32 v125, v125
	v_cvt_pk_bf16_f32 v120, v120, v121
	v_mul_f32_e32 v121, v126, v124
	v_mul_f32_e32 v121, v122, v121
	v_mul_f32_e32 v122, v127, v125
	v_mul_f32_e32 v122, v123, v122
	v_mul_f32_e32 v123, 0xbfb8aa3b, v116
	v_exp_f32_e32 v123, v123
	v_mul_f32_e32 v124, 0xbfb8aa3b, v117
	v_exp_f32_e32 v124, v124
	v_cvt_pk_bf16_f32 v121, v121, v122
	v_add_f32_e32 v122, 1.0, v123
	v_rcp_f32_e32 v122, v122
	v_add_f32_e32 v123, 1.0, v124
	s_ashr_i32 s25, s24, 31
	v_mov_b64_e32 v[144:145], s[6:7]
	v_rcp_f32_e32 v123, v123
	v_mad_i64_i32 v[152:153], s[26:27], v151, s55, v[144:145]
	s_lshl_b64 s[24:25], s[24:25], 1
	v_lshl_add_u64 v[152:153], v[152:153], 0, s[24:25]
	s_mov_b32 s13, s9
	v_lshl_add_u64 v[152:153], v[152:153], 0, s[12:13]
	v_mul_f32_e32 v116, v116, v122
	v_lshl_add_u64 v[152:153], v[152:153], 0, v[136:137]
	v_mul_f32_e32 v112, v112, v116
	v_mul_f32_e32 v116, v117, v123
	v_mul_f32_e32 v117, 0xbfb8aa3b, v118
	global_store_dwordx2 v[152:153], v[120:121], off
	v_exp_f32_e32 v117, v117
	v_mul_f32_e32 v120, 0xbfb8aa3b, v119
	v_exp_f32_e32 v120, v120
	v_mul_f32_e32 v113, v113, v116
	v_add_f32_e32 v116, 1.0, v117
	v_rcp_f32_e32 v116, v116
	v_add_f32_e32 v117, 1.0, v120
	v_rcp_f32_e32 v117, v117
	v_cvt_pk_bf16_f32 v112, v112, v113
	v_mul_f32_e32 v113, v118, v116
	v_mul_f32_e32 v113, v114, v113
	v_mul_f32_e32 v114, v119, v117
	v_mul_f32_e32 v114, v115, v114
	v_cvt_pk_bf16_f32 v113, v113, v114
	v_mul_f32_e32 v114, 0xbfb8aa3b, v108
	v_exp_f32_e32 v114, v114
	v_mul_f32_e32 v115, 0xbfb8aa3b, v109
	v_exp_f32_e32 v115, v115
	global_store_dwordx2 v[152:153], v[112:113], off offset:128
	v_add_f32_e32 v114, 1.0, v114
	v_rcp_f32_e32 v114, v114
	v_add_f32_e32 v115, 1.0, v115
	v_rcp_f32_e32 v115, v115
	v_or_b32_e32 v112, 16, v151
	v_mul_f32_e32 v108, v108, v114
	v_mul_f32_e32 v104, v104, v108
	v_mul_f32_e32 v108, v109, v115
	v_mul_f32_e32 v109, 0xbfb8aa3b, v110
	v_exp_f32_e32 v109, v109
	v_mul_f32_e32 v114, 0xbfb8aa3b, v111
	v_exp_f32_e32 v114, v114
	v_mul_f32_e32 v105, v105, v108
	v_add_f32_e32 v108, 1.0, v109
	v_rcp_f32_e32 v108, v108
	v_add_f32_e32 v109, 1.0, v114
	v_rcp_f32_e32 v109, v109
	v_cvt_pk_bf16_f32 v104, v104, v105
	v_mul_f32_e32 v105, v110, v108
	v_mul_f32_e32 v105, v106, v105
	v_mul_f32_e32 v106, v111, v109
	v_mul_f32_e32 v106, v107, v106
	v_mul_f32_e32 v107, 0xbfb8aa3b, v100
	v_exp_f32_e32 v107, v107
	v_mul_f32_e32 v108, 0xbfb8aa3b, v101
	v_exp_f32_e32 v108, v108
	v_cvt_pk_bf16_f32 v105, v105, v106
	v_add_f32_e32 v106, 1.0, v107
	v_rcp_f32_e32 v106, v106
	v_add_f32_e32 v107, 1.0, v108
	v_rcp_f32_e32 v107, v107
	v_mad_i64_i32 v[112:113], s[26:27], v112, s55, v[144:145]
	v_lshl_add_u64 v[112:113], v[112:113], 0, s[24:25]
	v_lshl_add_u64 v[112:113], v[112:113], 0, s[12:13]
	v_mul_f32_e32 v100, v100, v106
	v_lshl_add_u64 v[112:113], v[112:113], 0, v[136:137]
	v_mul_f32_e32 v96, v96, v100
	v_mul_f32_e32 v100, v101, v107
	v_mul_f32_e32 v101, 0xbfb8aa3b, v102
	global_store_dwordx2 v[112:113], v[104:105], off
	v_exp_f32_e32 v101, v101
	v_mul_f32_e32 v104, 0xbfb8aa3b, v103
	v_exp_f32_e32 v104, v104
	v_mul_f32_e32 v97, v97, v100
	v_add_f32_e32 v100, 1.0, v101
	v_rcp_f32_e32 v100, v100
	v_add_f32_e32 v101, 1.0, v104
	v_rcp_f32_e32 v101, v101
	v_cvt_pk_bf16_f32 v96, v96, v97
	v_mul_f32_e32 v97, v102, v100
	v_mul_f32_e32 v97, v98, v97
	v_mul_f32_e32 v98, v103, v101
	v_mul_f32_e32 v98, v99, v98
	v_cvt_pk_bf16_f32 v97, v97, v98
	v_mul_f32_e32 v98, 0xbfb8aa3b, v92
	v_exp_f32_e32 v98, v98
	v_mul_f32_e32 v99, 0xbfb8aa3b, v93
	v_exp_f32_e32 v99, v99
	global_store_dwordx2 v[112:113], v[96:97], off offset:128
	v_add_f32_e32 v98, 1.0, v98
	v_rcp_f32_e32 v98, v98
	v_add_f32_e32 v99, 1.0, v99
	v_rcp_f32_e32 v99, v99
	v_or_b32_e32 v96, 32, v151
	v_mul_f32_e32 v92, v92, v98
	v_mul_f32_e32 v88, v88, v92
	v_mul_f32_e32 v92, v93, v99
	v_mul_f32_e32 v93, 0xbfb8aa3b, v94
	v_exp_f32_e32 v93, v93
	v_mul_f32_e32 v98, 0xbfb8aa3b, v95
	v_exp_f32_e32 v98, v98
	v_mul_f32_e32 v89, v89, v92
	v_add_f32_e32 v92, 1.0, v93
	v_rcp_f32_e32 v92, v92
	v_add_f32_e32 v93, 1.0, v98
	v_rcp_f32_e32 v93, v93
	v_cvt_pk_bf16_f32 v88, v88, v89
	v_mul_f32_e32 v89, v94, v92
	v_mul_f32_e32 v89, v90, v89
	v_mul_f32_e32 v90, v95, v93
	v_mul_f32_e32 v90, v91, v90
	v_mul_f32_e32 v91, 0xbfb8aa3b, v84
	v_exp_f32_e32 v91, v91
	v_mul_f32_e32 v92, 0xbfb8aa3b, v85
	v_exp_f32_e32 v92, v92
	v_cvt_pk_bf16_f32 v89, v89, v90
	v_add_f32_e32 v90, 1.0, v91
	v_rcp_f32_e32 v90, v90
	v_add_f32_e32 v91, 1.0, v92
	v_rcp_f32_e32 v91, v91
	v_mad_i64_i32 v[96:97], s[26:27], v96, s55, v[144:145]
	v_lshl_add_u64 v[96:97], v[96:97], 0, s[24:25]
	v_lshl_add_u64 v[96:97], v[96:97], 0, s[12:13]
	v_mul_f32_e32 v84, v84, v90
	v_lshl_add_u64 v[96:97], v[96:97], 0, v[136:137]
	v_mul_f32_e32 v80, v80, v84
	v_mul_f32_e32 v84, v85, v91
	v_mul_f32_e32 v85, 0xbfb8aa3b, v86
	global_store_dwordx2 v[96:97], v[88:89], off
	v_exp_f32_e32 v85, v85
	v_mul_f32_e32 v88, 0xbfb8aa3b, v87
	v_exp_f32_e32 v88, v88
	v_mul_f32_e32 v81, v81, v84
	v_add_f32_e32 v84, 1.0, v85
	v_rcp_f32_e32 v84, v84
	v_add_f32_e32 v85, 1.0, v88
	v_rcp_f32_e32 v85, v85
	v_cvt_pk_bf16_f32 v80, v80, v81
	v_mul_f32_e32 v81, v86, v84
	v_mul_f32_e32 v81, v82, v81
	v_mul_f32_e32 v82, v87, v85
	v_mul_f32_e32 v82, v83, v82
	v_cvt_pk_bf16_f32 v81, v81, v82
	v_mul_f32_e32 v82, 0xbfb8aa3b, v76
	v_exp_f32_e32 v82, v82
	v_mul_f32_e32 v83, 0xbfb8aa3b, v77
	v_exp_f32_e32 v83, v83
	global_store_dwordx2 v[96:97], v[80:81], off offset:128
	v_add_f32_e32 v82, 1.0, v82
	v_rcp_f32_e32 v82, v82
	v_add_f32_e32 v83, 1.0, v83
	v_rcp_f32_e32 v83, v83
	v_or_b32_e32 v80, 48, v151
	v_mul_f32_e32 v76, v76, v82
	v_mul_f32_e32 v72, v72, v76
	v_mul_f32_e32 v76, v77, v83
	v_mul_f32_e32 v77, 0xbfb8aa3b, v78
	v_exp_f32_e32 v77, v77
	v_mul_f32_e32 v82, 0xbfb8aa3b, v79
	v_exp_f32_e32 v82, v82
	v_mul_f32_e32 v73, v73, v76
	v_add_f32_e32 v76, 1.0, v77
	v_rcp_f32_e32 v76, v76
	v_add_f32_e32 v77, 1.0, v82
	v_rcp_f32_e32 v77, v77
	v_cvt_pk_bf16_f32 v72, v72, v73
	v_mul_f32_e32 v73, v78, v76
	v_mul_f32_e32 v73, v74, v73
	v_mul_f32_e32 v74, v79, v77
	v_mul_f32_e32 v74, v75, v74
	v_mul_f32_e32 v75, 0xbfb8aa3b, v68
	v_exp_f32_e32 v75, v75
	v_mul_f32_e32 v76, 0xbfb8aa3b, v69
	v_exp_f32_e32 v76, v76
	v_cvt_pk_bf16_f32 v73, v73, v74
	v_add_f32_e32 v74, 1.0, v75
	v_rcp_f32_e32 v74, v74
	v_add_f32_e32 v75, 1.0, v76
	v_rcp_f32_e32 v75, v75
	v_mad_i64_i32 v[80:81], s[26:27], v80, s55, v[144:145]
	v_lshl_add_u64 v[80:81], v[80:81], 0, s[24:25]
	v_lshl_add_u64 v[80:81], v[80:81], 0, s[12:13]
	v_mul_f32_e32 v68, v68, v74
	v_lshl_add_u64 v[80:81], v[80:81], 0, v[136:137]
	v_mul_f32_e32 v64, v64, v68
	v_mul_f32_e32 v68, v69, v75
	v_mul_f32_e32 v69, 0xbfb8aa3b, v70
	global_store_dwordx2 v[80:81], v[72:73], off
	v_exp_f32_e32 v69, v69
	v_mul_f32_e32 v72, 0xbfb8aa3b, v71
	v_exp_f32_e32 v72, v72
	v_mul_f32_e32 v65, v65, v68
	v_add_f32_e32 v68, 1.0, v69
	v_rcp_f32_e32 v68, v68
	v_add_f32_e32 v69, 1.0, v72
	v_rcp_f32_e32 v69, v69
	v_cvt_pk_bf16_f32 v64, v64, v65
	v_mul_f32_e32 v65, v70, v68
	v_mul_f32_e32 v65, v66, v65
	v_mul_f32_e32 v66, v71, v69
	v_mul_f32_e32 v66, v67, v66
	v_cvt_pk_bf16_f32 v65, v65, v66
	v_mul_f32_e32 v66, 0xbfb8aa3b, v60
	v_exp_f32_e32 v66, v66
	v_mul_f32_e32 v67, 0xbfb8aa3b, v61
	v_exp_f32_e32 v67, v67
	global_store_dwordx2 v[80:81], v[64:65], off offset:128
	v_add_f32_e32 v66, 1.0, v66
	v_rcp_f32_e32 v66, v66
	v_add_f32_e32 v67, 1.0, v67
	v_rcp_f32_e32 v67, v67
	v_add_u32_e32 v64, 0x80, v151
	v_mul_f32_e32 v60, v60, v66
	v_mul_f32_e32 v56, v56, v60
	v_mul_f32_e32 v60, v61, v67
	v_mul_f32_e32 v61, 0xbfb8aa3b, v62
	v_exp_f32_e32 v61, v61
	v_mul_f32_e32 v66, 0xbfb8aa3b, v63
	v_exp_f32_e32 v66, v66
	v_mul_f32_e32 v57, v57, v60
	v_add_f32_e32 v60, 1.0, v61
	v_rcp_f32_e32 v60, v60
	v_add_f32_e32 v61, 1.0, v66
	v_rcp_f32_e32 v61, v61
	v_cvt_pk_bf16_f32 v56, v56, v57
	v_mul_f32_e32 v57, v62, v60
	v_mul_f32_e32 v57, v58, v57
	v_mul_f32_e32 v58, v63, v61
	v_mul_f32_e32 v58, v59, v58
	v_mul_f32_e32 v59, 0xbfb8aa3b, v52
	v_exp_f32_e32 v59, v59
	v_mul_f32_e32 v60, 0xbfb8aa3b, v53
	v_exp_f32_e32 v60, v60
	v_cvt_pk_bf16_f32 v57, v57, v58
	v_add_f32_e32 v58, 1.0, v59
	v_rcp_f32_e32 v58, v58
	v_add_f32_e32 v59, 1.0, v60
	v_rcp_f32_e32 v59, v59
	v_mad_i64_i32 v[64:65], s[26:27], v64, s55, v[144:145]
	v_lshl_add_u64 v[64:65], v[64:65], 0, s[24:25]
	v_lshl_add_u64 v[64:65], v[64:65], 0, s[12:13]
	v_mul_f32_e32 v52, v52, v58
	v_lshl_add_u64 v[64:65], v[64:65], 0, v[136:137]
	v_mul_f32_e32 v48, v48, v52
	v_mul_f32_e32 v52, v53, v59
	v_mul_f32_e32 v53, 0xbfb8aa3b, v54
	global_store_dwordx2 v[64:65], v[56:57], off
	v_exp_f32_e32 v53, v53
	v_mul_f32_e32 v56, 0xbfb8aa3b, v55
	v_exp_f32_e32 v56, v56
	v_mul_f32_e32 v49, v49, v52
	v_add_f32_e32 v52, 1.0, v53
	v_rcp_f32_e32 v52, v52
	v_add_f32_e32 v53, 1.0, v56
	v_rcp_f32_e32 v53, v53
	v_cvt_pk_bf16_f32 v48, v48, v49
	v_mul_f32_e32 v49, v54, v52
	v_mul_f32_e32 v49, v50, v49
	v_mul_f32_e32 v50, v55, v53
	v_mul_f32_e32 v50, v51, v50
	v_cvt_pk_bf16_f32 v49, v49, v50
	v_mul_f32_e32 v50, 0xbfb8aa3b, v44
	v_exp_f32_e32 v50, v50
	v_mul_f32_e32 v51, 0xbfb8aa3b, v45
	v_exp_f32_e32 v51, v51
	global_store_dwordx2 v[64:65], v[48:49], off offset:128
	v_add_f32_e32 v50, 1.0, v50
	v_rcp_f32_e32 v50, v50
	v_add_f32_e32 v51, 1.0, v51
	v_rcp_f32_e32 v51, v51
	v_add_u32_e32 v48, 0x90, v151
	v_mul_f32_e32 v44, v44, v50
	v_mul_f32_e32 v40, v40, v44
	v_mul_f32_e32 v44, v45, v51
	v_mul_f32_e32 v45, 0xbfb8aa3b, v46
	v_exp_f32_e32 v45, v45
	v_mul_f32_e32 v50, 0xbfb8aa3b, v47
	v_exp_f32_e32 v50, v50
	v_mul_f32_e32 v41, v41, v44
	v_add_f32_e32 v44, 1.0, v45
	v_rcp_f32_e32 v44, v44
	v_add_f32_e32 v45, 1.0, v50
	v_rcp_f32_e32 v45, v45
	v_cvt_pk_bf16_f32 v40, v40, v41
	v_mul_f32_e32 v41, v46, v44
	v_mul_f32_e32 v41, v42, v41
	v_mul_f32_e32 v42, v47, v45
	v_mul_f32_e32 v42, v43, v42
	v_mul_f32_e32 v43, 0xbfb8aa3b, v36
	v_exp_f32_e32 v43, v43
	v_mul_f32_e32 v44, 0xbfb8aa3b, v37
	v_exp_f32_e32 v44, v44
	v_cvt_pk_bf16_f32 v41, v41, v42
	v_add_f32_e32 v42, 1.0, v43
	v_rcp_f32_e32 v42, v42
	v_add_f32_e32 v43, 1.0, v44
	v_rcp_f32_e32 v43, v43
	v_mad_i64_i32 v[48:49], s[26:27], v48, s55, v[144:145]
	v_lshl_add_u64 v[48:49], v[48:49], 0, s[24:25]
	v_lshl_add_u64 v[48:49], v[48:49], 0, s[12:13]
	v_mul_f32_e32 v36, v36, v42
	v_lshl_add_u64 v[48:49], v[48:49], 0, v[136:137]
	v_mul_f32_e32 v32, v32, v36
	v_mul_f32_e32 v36, v37, v43
	v_mul_f32_e32 v37, 0xbfb8aa3b, v38
	global_store_dwordx2 v[48:49], v[40:41], off
	v_exp_f32_e32 v37, v37
	v_mul_f32_e32 v40, 0xbfb8aa3b, v39
	v_exp_f32_e32 v40, v40
	v_mul_f32_e32 v33, v33, v36
	v_add_f32_e32 v36, 1.0, v37
	v_rcp_f32_e32 v36, v36
	v_add_f32_e32 v37, 1.0, v40
	v_rcp_f32_e32 v37, v37
	v_cvt_pk_bf16_f32 v32, v32, v33
	v_mul_f32_e32 v33, v38, v36
	v_mul_f32_e32 v33, v34, v33
	v_mul_f32_e32 v34, v39, v37
	v_mul_f32_e32 v34, v35, v34
	v_cvt_pk_bf16_f32 v33, v33, v34
	v_mul_f32_e32 v34, 0xbfb8aa3b, v28
	v_exp_f32_e32 v34, v34
	v_mul_f32_e32 v35, 0xbfb8aa3b, v29
	v_exp_f32_e32 v35, v35
	global_store_dwordx2 v[48:49], v[32:33], off offset:128
	v_add_f32_e32 v34, 1.0, v34
	v_rcp_f32_e32 v34, v34
	v_add_f32_e32 v35, 1.0, v35
	v_rcp_f32_e32 v35, v35
	v_add_u32_e32 v32, 0xa0, v151
	v_mul_f32_e32 v28, v28, v34
	v_mul_f32_e32 v24, v24, v28
	v_mul_f32_e32 v28, v29, v35
	v_mul_f32_e32 v29, 0xbfb8aa3b, v30
	v_exp_f32_e32 v29, v29
	v_mul_f32_e32 v34, 0xbfb8aa3b, v31
	v_exp_f32_e32 v34, v34
	v_mul_f32_e32 v25, v25, v28
	v_add_f32_e32 v28, 1.0, v29
	v_rcp_f32_e32 v28, v28
	v_add_f32_e32 v29, 1.0, v34
	v_rcp_f32_e32 v29, v29
	v_cvt_pk_bf16_f32 v24, v24, v25
	v_mul_f32_e32 v25, v30, v28
	v_mul_f32_e32 v25, v26, v25
	v_mul_f32_e32 v26, v31, v29
	v_mul_f32_e32 v26, v27, v26
	v_mul_f32_e32 v27, 0xbfb8aa3b, v20
	v_exp_f32_e32 v27, v27
	v_mul_f32_e32 v28, 0xbfb8aa3b, v21
	v_exp_f32_e32 v28, v28
	v_cvt_pk_bf16_f32 v25, v25, v26
	v_add_f32_e32 v26, 1.0, v27
	v_rcp_f32_e32 v26, v26
	v_add_f32_e32 v27, 1.0, v28
	v_rcp_f32_e32 v27, v27
	v_mad_i64_i32 v[32:33], s[26:27], v32, s55, v[144:145]
	v_lshl_add_u64 v[32:33], v[32:33], 0, s[24:25]
	v_lshl_add_u64 v[32:33], v[32:33], 0, s[12:13]
	v_mul_f32_e32 v20, v20, v26
	v_lshl_add_u64 v[32:33], v[32:33], 0, v[136:137]
	v_mul_f32_e32 v16, v16, v20
	v_mul_f32_e32 v20, v21, v27
	v_mul_f32_e32 v21, 0xbfb8aa3b, v22
	global_store_dwordx2 v[32:33], v[24:25], off
	v_exp_f32_e32 v21, v21
	v_mul_f32_e32 v24, 0xbfb8aa3b, v23
	v_exp_f32_e32 v24, v24
	v_mul_f32_e32 v17, v17, v20
	v_add_f32_e32 v20, 1.0, v21
	v_rcp_f32_e32 v20, v20
	v_add_f32_e32 v21, 1.0, v24
	v_rcp_f32_e32 v21, v21
	v_cvt_pk_bf16_f32 v16, v16, v17
	v_mul_f32_e32 v17, v22, v20
	v_mul_f32_e32 v17, v18, v17
	v_mul_f32_e32 v18, v23, v21
	v_mul_f32_e32 v18, v19, v18
	v_cvt_pk_bf16_f32 v17, v17, v18
	v_mul_f32_e32 v18, 0xbfb8aa3b, v12
	v_exp_f32_e32 v18, v18
	v_mul_f32_e32 v19, 0xbfb8aa3b, v13
	v_exp_f32_e32 v19, v19
	global_store_dwordx2 v[32:33], v[16:17], off offset:128
	v_add_f32_e32 v18, 1.0, v18
	v_rcp_f32_e32 v18, v18
	v_add_f32_e32 v19, 1.0, v19
	v_rcp_f32_e32 v19, v19
	v_add_u32_e32 v16, 0xb0, v151
	v_mul_f32_e32 v12, v12, v18
	v_mul_f32_e32 v8, v8, v12
	v_mul_f32_e32 v12, v13, v19
	v_mul_f32_e32 v13, 0xbfb8aa3b, v14
	v_exp_f32_e32 v13, v13
	v_mul_f32_e32 v18, 0xbfb8aa3b, v15
	v_exp_f32_e32 v18, v18
	v_mul_f32_e32 v9, v9, v12
	v_add_f32_e32 v12, 1.0, v13
	v_rcp_f32_e32 v12, v12
	v_add_f32_e32 v13, 1.0, v18
	v_rcp_f32_e32 v13, v13
	v_cvt_pk_bf16_f32 v8, v8, v9
	v_mul_f32_e32 v9, v14, v12
	v_mul_f32_e32 v9, v10, v9
	v_mul_f32_e32 v10, v15, v13
	v_mul_f32_e32 v10, v11, v10
	v_mul_f32_e32 v11, 0xbfb8aa3b, v4
	v_exp_f32_e32 v11, v11
	v_mul_f32_e32 v12, 0xbfb8aa3b, v5
	v_exp_f32_e32 v12, v12
	v_cvt_pk_bf16_f32 v9, v9, v10
	v_add_f32_e32 v10, 1.0, v11
	v_rcp_f32_e32 v10, v10
	v_add_f32_e32 v11, 1.0, v12
	v_rcp_f32_e32 v11, v11
	v_mad_i64_i32 v[16:17], s[26:27], v16, s55, v[144:145]
	v_lshl_add_u64 v[16:17], v[16:17], 0, s[24:25]
	v_lshl_add_u64 v[16:17], v[16:17], 0, s[12:13]
	v_mul_f32_e32 v4, v4, v10
	v_lshl_add_u64 v[16:17], v[16:17], 0, v[136:137]
	v_mul_f32_e32 v0, v0, v4
	v_mul_f32_e32 v4, v5, v11
	v_mul_f32_e32 v5, 0xbfb8aa3b, v6
	global_store_dwordx2 v[16:17], v[8:9], off
	v_exp_f32_e32 v5, v5
	v_mul_f32_e32 v8, 0xbfb8aa3b, v7
	v_exp_f32_e32 v8, v8
	v_mul_f32_e32 v1, v1, v4
	v_add_f32_e32 v4, 1.0, v5
	v_rcp_f32_e32 v4, v4
	v_add_f32_e32 v5, 1.0, v8
	v_rcp_f32_e32 v5, v5
	v_cvt_pk_bf16_f32 v0, v0, v1
	v_mul_f32_e32 v1, v6, v4
	v_mul_f32_e32 v1, v2, v1
	v_mul_f32_e32 v2, v7, v5
	s_and_b64 vcc, exec, s[18:19]
	s_mov_b32 s13, s16
	s_mov_b32 s24, s14
	s_mov_b64 s[28:29], s[22:23]
	s_mov_b64 s[26:27], s[20:21]
	v_mul_f32_e32 v2, v3, v2
	v_cvt_pk_bf16_f32 v1, v1, v2
	global_store_dwordx2 v[16:17], v[0:1], off offset:128
	s_cbranch_vccz .LBB0_1062
	s_waitcnt vmcnt(0)
	s_cmpk_gt_u32 s2, 0xff
	s_cbranch_scc1 .LBB0_1069
	s_barrier
